# stack2 + halo mini-GEMM: prefetch hoist and LDS staging writes moved into the middle of the MFMA sequence
# speedup vs baseline: 1.0079x; 1.0046x over previous
; #define LAS __attribute__((address_space(3)))
; __device__ __forceinline__ void halo_gemm_unit(int unit, int tid, int lane, int wave, LAS unsigned char* lds, const bf16_t* __restrict__ XBp, const bf16_t* __restrict__ Wup, bf16_t* __restrict__ HALOp) {
;     ...
;     for (int c = 0; c < 16; c += 2) {
;         { const int k2 = (c + 2 < 16) ? 64 * (c + 2) : 0;
; #pragma unroll
;           for (int i = 0; i < 2; ++i) ra0[i] = *(const v4u*)(gA[i] + k2);
; #pragma unroll
;           for (int i = 0; i < 4; ++i) rb0[i] = *(const v4u*)(gB[i] + k2);
;           HG_COMPUTE(lds);
; #pragma unroll
;           for (int i = 0; i < 2; ++i) *(LAS v4u*)(lds + HG_STAGE + lA[i]) = ra1[i];
; #pragma unroll
;           for (int i = 0; i < 4; ++i) *(LAS v4u*)(lds + HG_STAGE + lB[i]) = rb1[i];
;           __syncthreads(); }
;         { const int k3 = (c + 3 < 16) ? 64 * (c + 3) : 0;
; #pragma unroll
;           for (int i = 0; i < 2; ++i) ra1[i] = *(const v4u*)(gA[i] + k3);
; #pragma unroll
;           for (int i = 0; i < 4; ++i) rb1[i] = *(const v4u*)(gB[i] + k3);
;           HG_COMPUTE(lds + HG_STAGE);
;           if (c + 2 < 16) {
; #pragma unroll
;               for (int i = 0; i < 2; ++i) *(LAS v4u*)(lds + lA[i]) = ra0[i];
; #pragma unroll
;               for (int i = 0; i < 4; ++i) *(LAS v4u*)(lds + lB[i]) = rb0[i];
;           }
;           __syncthreads(); }
;     }
.LBB0_684:
	s_cmp_gt_u32 s12, 13
	s_cselect_b64 s[8:9], -1, 0
	s_sub_i32 s0, s10, 64
	s_cmp_lt_u32 s12, 14
	s_cselect_b32 s6, s0, 0
	s_lshl_b64 s[0:1], s[6:7], 1
	s_cmp_lt_u32 s12, 13
	s_cselect_b32 s6, s10, 0
	v_lshl_add_u64 v[110:111], v[124:125], 0, s[0:1]
	v_lshl_add_u64 v[90:91], v[114:115], 0, s[0:1]
	v_lshl_add_u64 v[94:95], v[116:117], 0, s[0:1]
	v_lshl_add_u64 v[106:107], v[122:123], 0, s[0:1]
	v_lshl_add_u64 v[98:99], v[118:119], 0, s[0:1]
	v_lshl_add_u64 v[102:103], v[120:121], 0, s[0:1]
	global_load_dwordx4 v[90:93], v[90:91], off
	s_nop 0
	global_load_dwordx4 v[94:97], v[94:95], off
	s_nop 0
	global_load_dwordx4 v[98:101], v[98:99], off
	s_nop 0
	global_load_dwordx4 v[102:105], v[102:103], off
	s_nop 0
	global_load_dwordx4 v[106:109], v[106:107], off
	s_nop 0
	global_load_dwordx4 v[110:113], v[110:111], off
	s_nop 0
	v_add_u32_e32 v139, 0, v132
	ds_read_b128 v[156:159], v139 offset:18432
	ds_read_b128 v[160:163], v133
	ds_read_b128 v[164:167], v133 offset:32
	ds_read_b128 v[168:171], v139 offset:18464
	ds_read_b128 v[172:175], v139 offset:23040
	ds_read_b128 v[176:179], v139 offset:23072
	s_waitcnt lgkmcnt(4)
	v_mfma_f32_32x32x16_bf16 v[50:65], v[156:159], v[160:163], v[50:65]
	s_waitcnt lgkmcnt(1)
	v_mfma_f32_32x32x16_bf16 v[34:49], v[172:175], v[160:163], v[34:49]
	ds_read_b128 v[160:163], v133 offset:4608
	ds_read_b128 v[140:143], v133 offset:4640
	s_and_b64 vcc, exec, s[8:9]
	s_waitcnt lgkmcnt(1)
	v_mfma_f32_32x32x16_bf16 v[18:33], v[156:159], v[160:163], v[18:33]
	v_mfma_f32_32x32x16_bf16 v[2:17], v[172:175], v[160:163], v[2:17]
	v_mfma_f32_32x32x16_bf16 v[50:65], v[168:171], v[164:167], v[50:65]
	v_mfma_f32_32x32x16_bf16 v[34:49], v[176:179], v[164:167], v[34:49]
	s_waitcnt lgkmcnt(0)
	v_mfma_f32_32x32x16_bf16 v[18:33], v[168:171], v[140:143], v[18:33]
	s_waitcnt vmcnt(11)
	ds_write_b128 v128, v[66:69] offset:55296
	s_waitcnt vmcnt(10)
	ds_write_b128 v129, v[70:73] offset:55296
	s_waitcnt vmcnt(9)
	ds_write_b128 v134, v[74:77] offset:55296
	s_waitcnt vmcnt(8)
	ds_write_b128 v135, v[78:81] offset:55296
	s_waitcnt vmcnt(6)
	ds_write_b128 v136, v[86:89] offset:55296
	ds_write_b128 v137, v[82:85] offset:55296
	ds_read_b128 v[156:159], v139 offset:18496
	ds_read_b128 v[160:163], v133 offset:64
	ds_read_b128 v[164:167], v133 offset:96
	ds_read_b128 v[168:171], v139 offset:18528
	v_mfma_f32_32x32x16_bf16 v[2:17], v[176:179], v[140:143], v[2:17]
	ds_read_b128 v[172:175], v139 offset:23104
	ds_read_b128 v[140:143], v139 offset:23136
	s_waitcnt lgkmcnt(4)
	v_mfma_f32_32x32x16_bf16 v[50:65], v[156:159], v[160:163], v[50:65]
	s_waitcnt lgkmcnt(1)
	v_mfma_f32_32x32x16_bf16 v[34:49], v[172:175], v[160:163], v[34:49]
	ds_read_b128 v[160:163], v133 offset:4672
	ds_read_b128 v[146:149], v133 offset:4704
	s_waitcnt lgkmcnt(1)
	v_mfma_f32_32x32x16_bf16 v[18:33], v[156:159], v[160:163], v[18:33]
	v_mfma_f32_32x32x16_bf16 v[2:17], v[172:175], v[160:163], v[2:17]
	v_mfma_f32_32x32x16_bf16 v[50:65], v[168:171], v[164:167], v[50:65]
	v_mfma_f32_32x32x16_bf16 v[34:49], v[140:143], v[164:167], v[34:49]
	s_waitcnt lgkmcnt(0)
	v_mfma_f32_32x32x16_bf16 v[18:33], v[168:171], v[146:149], v[18:33]
	s_waitcnt lgkmcnt(0)
	s_barrier
	s_lshl_b64 s[0:1], s[6:7], 1
	v_lshl_add_u64 v[150:151], v[124:125], 0, s[0:1]
	v_lshl_add_u64 v[86:87], v[122:123], 0, s[0:1]
	v_lshl_add_u64 v[66:67], v[114:115], 0, s[0:1]
	v_lshl_add_u64 v[70:71], v[116:117], 0, s[0:1]
	v_lshl_add_u64 v[78:79], v[120:121], 0, s[0:1]
	v_lshl_add_u64 v[74:75], v[118:119], 0, s[0:1]
	global_load_dwordx4 v[66:69], v[66:67], off
	s_nop 0
	global_load_dwordx4 v[70:73], v[70:71], off
	s_nop 0
	global_load_dwordx4 v[74:77], v[74:75], off
	s_nop 0
	global_load_dwordx4 v[78:81], v[78:79], off
	s_nop 0
	global_load_dwordx4 v[86:89], v[86:87], off
	s_nop 0
	global_load_dwordx4 v[82:85], v[150:151], off
	s_nop 0
	v_mfma_f32_32x32x16_bf16 v[2:17], v[140:143], v[146:149], v[2:17]
	ds_read_b128 v[180:183], v138 offset:55296
	ds_read_b128 v[184:187], v133 offset:55296
	ds_read_b128 v[188:191], v133 offset:55328
	ds_read_b128 v[192:195], v138 offset:55328
	ds_read_b128 v[196:199], v138 offset:59904
	ds_read_b128 v[200:203], v138 offset:59936
	s_waitcnt lgkmcnt(4)
	v_mfma_f32_32x32x16_bf16 v[50:65], v[180:183], v[184:187], v[50:65]
	s_waitcnt lgkmcnt(1)
	v_mfma_f32_32x32x16_bf16 v[34:49], v[196:199], v[184:187], v[34:49]
	ds_read_b128 v[184:187], v133 offset:59904
	ds_read_b128 v[140:143], v133 offset:59936
	s_waitcnt lgkmcnt(1)
	v_mfma_f32_32x32x16_bf16 v[18:33], v[180:183], v[184:187], v[18:33]
	v_mfma_f32_32x32x16_bf16 v[2:17], v[196:199], v[184:187], v[2:17]
	v_mfma_f32_32x32x16_bf16 v[50:65], v[192:195], v[188:191], v[50:65]
	v_mfma_f32_32x32x16_bf16 v[34:49], v[200:203], v[188:191], v[34:49]
	s_cbranch_vccnz .Lhgw_skip_7
	s_waitcnt vmcnt(11)
	ds_write_b128 v128, v[90:93]
	s_waitcnt vmcnt(10)
	ds_write_b128 v129, v[94:97]
	s_waitcnt vmcnt(9)
	ds_write_b128 v128, v[98:101] offset:18432
	s_waitcnt vmcnt(8)
	ds_write_b128 v129, v[102:105] offset:18432
	s_waitcnt vmcnt(7)
	ds_write_b128 v130, v[106:109] offset:18432
	s_waitcnt vmcnt(6)
	ds_write_b128 v131, v[110:113] offset:18432
.Lhgw_skip_7:
	ds_read_b128 v[180:183], v138 offset:55360
	ds_read_b128 v[184:187], v133 offset:55360
	ds_read_b128 v[188:191], v133 offset:55392
	ds_read_b128 v[196:199], v138 offset:55392
	s_waitcnt lgkmcnt(4)
	v_mfma_f32_32x32x16_bf16 v[18:33], v[192:195], v[140:143], v[18:33]
	v_mfma_f32_32x32x16_bf16 v[2:17], v[200:203], v[140:143], v[2:17]
	ds_read_b128 v[192:195], v138 offset:59968
	ds_read_b128 v[140:143], v138 offset:60000
	s_waitcnt lgkmcnt(4)
	v_mfma_f32_32x32x16_bf16 v[50:65], v[180:183], v[184:187], v[50:65]
	s_waitcnt lgkmcnt(1)
	v_mfma_f32_32x32x16_bf16 v[34:49], v[192:195], v[184:187], v[34:49]
	ds_read_b128 v[184:187], v133 offset:59968
	ds_read_b128 v[146:149], v133 offset:60000
	s_waitcnt lgkmcnt(1)
	v_mfma_f32_32x32x16_bf16 v[18:33], v[180:183], v[184:187], v[18:33]
	v_mfma_f32_32x32x16_bf16 v[2:17], v[192:195], v[184:187], v[2:17]
	v_mfma_f32_32x32x16_bf16 v[50:65], v[196:199], v[188:191], v[50:65]
	v_mfma_f32_32x32x16_bf16 v[34:49], v[140:143], v[188:191], v[34:49]
	s_waitcnt lgkmcnt(0)
	v_mfma_f32_32x32x16_bf16 v[18:33], v[196:199], v[146:149], v[18:33]
	v_mfma_f32_32x32x16_bf16 v[2:17], v[140:143], v[146:149], v[2:17]
	s_branch .LBB0_683

; #define LAS __attribute__((address_space(3)))
; __device__ __forceinline__ void halo_gemm_unit(int unit, int tid, int lane, int wave, LAS unsigned char* lds, const bf16_t* __restrict__ XBp, const bf16_t* __restrict__ Wup, bf16_t* __restrict__ HALOp) {
;     ...
;     for (int c = 0; c < 16; c += 2) {
;         { const int k2 = (c + 2 < 16) ? 64 * (c + 2) : 0;
; #pragma unroll
;           for (int i = 0; i < 2; ++i) ra0[i] = *(const v4u*)(gA[i] + k2);
; #pragma unroll
;           for (int i = 0; i < 4; ++i) rb0[i] = *(const v4u*)(gB[i] + k2);
;           HG_COMPUTE(lds);
; #pragma unroll
;           for (int i = 0; i < 2; ++i) *(LAS v4u*)(lds + HG_STAGE + lA[i]) = ra1[i];
; #pragma unroll
;           for (int i = 0; i < 4; ++i) *(LAS v4u*)(lds + HG_STAGE + lB[i]) = rb1[i];
;           __syncthreads(); }
;         { const int k3 = (c + 3 < 16) ? 64 * (c + 3) : 0;
; #pragma unroll
;           for (int i = 0; i < 2; ++i) ra1[i] = *(const v4u*)(gA[i] + k3);
; #pragma unroll
;           for (int i = 0; i < 4; ++i) rb1[i] = *(const v4u*)(gB[i] + k3);
;           HG_COMPUTE(lds + HG_STAGE);
;           if (c + 2 < 16) {
; #pragma unroll
;               for (int i = 0; i < 2; ++i) *(LAS v4u*)(lds + lA[i]) = ra0[i];
; #pragma unroll
;               for (int i = 0; i < 4; ++i) *(LAS v4u*)(lds + lB[i]) = rb0[i];
;           }
;           __syncthreads(); }
;     }
.LBB0_1756:
	s_cmp_gt_u32 s14, 13
	s_cselect_b64 s[10:11], -1, 0
	s_sub_i32 s0, s12, 64
	s_cmp_lt_u32 s14, 14
	s_cselect_b32 s8, s0, 0
	s_lshl_b64 s[0:1], s[8:9], 1
	s_cmp_lt_u32 s14, 13
	s_cselect_b32 s8, s12, 0
	v_lshl_add_u64 v[110:111], v[124:125], 0, s[0:1]
	v_lshl_add_u64 v[90:91], v[114:115], 0, s[0:1]
	v_lshl_add_u64 v[94:95], v[116:117], 0, s[0:1]
	v_lshl_add_u64 v[106:107], v[122:123], 0, s[0:1]
	v_lshl_add_u64 v[98:99], v[118:119], 0, s[0:1]
	v_lshl_add_u64 v[102:103], v[120:121], 0, s[0:1]
	global_load_dwordx4 v[90:93], v[90:91], off
	s_nop 0
	global_load_dwordx4 v[94:97], v[94:95], off
	s_nop 0
	global_load_dwordx4 v[98:101], v[98:99], off
	s_nop 0
	global_load_dwordx4 v[102:105], v[102:103], off
	s_nop 0
	global_load_dwordx4 v[106:109], v[106:107], off
	s_nop 0
	global_load_dwordx4 v[110:113], v[110:111], off
	s_nop 0
	v_add_u32_e32 v139, 0, v132
	ds_read_b128 v[156:159], v139 offset:18432
	ds_read_b128 v[160:163], v133
	ds_read_b128 v[164:167], v133 offset:32
	ds_read_b128 v[168:171], v139 offset:18464
	ds_read_b128 v[172:175], v139 offset:23040
	ds_read_b128 v[176:179], v139 offset:23072
	s_waitcnt lgkmcnt(4)
	v_mfma_f32_32x32x16_bf16 v[50:65], v[156:159], v[160:163], v[50:65]
	s_waitcnt lgkmcnt(1)
	v_mfma_f32_32x32x16_bf16 v[34:49], v[172:175], v[160:163], v[34:49]
	ds_read_b128 v[160:163], v133 offset:4608
	ds_read_b128 v[140:143], v133 offset:4640
	s_and_b64 vcc, exec, s[10:11]
	s_waitcnt lgkmcnt(1)
	v_mfma_f32_32x32x16_bf16 v[18:33], v[156:159], v[160:163], v[18:33]
	v_mfma_f32_32x32x16_bf16 v[2:17], v[172:175], v[160:163], v[2:17]
	v_mfma_f32_32x32x16_bf16 v[50:65], v[168:171], v[164:167], v[50:65]
	v_mfma_f32_32x32x16_bf16 v[34:49], v[176:179], v[164:167], v[34:49]
	s_waitcnt lgkmcnt(0)
	v_mfma_f32_32x32x16_bf16 v[18:33], v[168:171], v[140:143], v[18:33]
	s_waitcnt vmcnt(11)
	ds_write_b128 v128, v[66:69] offset:55296
	s_waitcnt vmcnt(10)
	ds_write_b128 v129, v[70:73] offset:55296
	s_waitcnt vmcnt(9)
	ds_write_b128 v134, v[74:77] offset:55296
	s_waitcnt vmcnt(8)
	ds_write_b128 v135, v[78:81] offset:55296
	s_waitcnt vmcnt(6)
	ds_write_b128 v136, v[86:89] offset:55296
	ds_write_b128 v137, v[82:85] offset:55296
	ds_read_b128 v[156:159], v139 offset:18496
	ds_read_b128 v[160:163], v133 offset:64
	ds_read_b128 v[164:167], v133 offset:96
	ds_read_b128 v[168:171], v139 offset:18528
	v_mfma_f32_32x32x16_bf16 v[2:17], v[176:179], v[140:143], v[2:17]
	ds_read_b128 v[172:175], v139 offset:23104
	ds_read_b128 v[140:143], v139 offset:23136
	s_waitcnt lgkmcnt(4)
	v_mfma_f32_32x32x16_bf16 v[50:65], v[156:159], v[160:163], v[50:65]
	s_waitcnt lgkmcnt(1)
	v_mfma_f32_32x32x16_bf16 v[34:49], v[172:175], v[160:163], v[34:49]
	ds_read_b128 v[160:163], v133 offset:4672
	ds_read_b128 v[144:147], v133 offset:4704
	s_waitcnt lgkmcnt(1)
	v_mfma_f32_32x32x16_bf16 v[18:33], v[156:159], v[160:163], v[18:33]
	v_mfma_f32_32x32x16_bf16 v[2:17], v[172:175], v[160:163], v[2:17]
	v_mfma_f32_32x32x16_bf16 v[50:65], v[168:171], v[164:167], v[50:65]
	v_mfma_f32_32x32x16_bf16 v[34:49], v[140:143], v[164:167], v[34:49]
	s_waitcnt lgkmcnt(0)
	v_mfma_f32_32x32x16_bf16 v[18:33], v[168:171], v[144:147], v[18:33]
	s_waitcnt lgkmcnt(0)
	s_barrier
	s_lshl_b64 s[0:1], s[8:9], 1
	v_lshl_add_u64 v[148:149], v[124:125], 0, s[0:1]
	v_lshl_add_u64 v[86:87], v[122:123], 0, s[0:1]
	v_lshl_add_u64 v[66:67], v[114:115], 0, s[0:1]
	v_lshl_add_u64 v[70:71], v[116:117], 0, s[0:1]
	v_lshl_add_u64 v[78:79], v[120:121], 0, s[0:1]
	v_lshl_add_u64 v[74:75], v[118:119], 0, s[0:1]
	global_load_dwordx4 v[66:69], v[66:67], off
	s_nop 0
	global_load_dwordx4 v[70:73], v[70:71], off
	s_nop 0
	global_load_dwordx4 v[74:77], v[74:75], off
	s_nop 0
	global_load_dwordx4 v[78:81], v[78:79], off
	s_nop 0
	global_load_dwordx4 v[86:89], v[86:87], off
	s_nop 0
	global_load_dwordx4 v[82:85], v[148:149], off
	s_nop 0
	v_mfma_f32_32x32x16_bf16 v[2:17], v[140:143], v[144:147], v[2:17]
	ds_read_b128 v[180:183], v138 offset:55296
	ds_read_b128 v[184:187], v133 offset:55296
	ds_read_b128 v[188:191], v133 offset:55328
	ds_read_b128 v[192:195], v138 offset:55328
	ds_read_b128 v[196:199], v138 offset:59904
	ds_read_b128 v[200:203], v138 offset:59936
	s_waitcnt lgkmcnt(4)
	v_mfma_f32_32x32x16_bf16 v[50:65], v[180:183], v[184:187], v[50:65]
	s_waitcnt lgkmcnt(1)
	v_mfma_f32_32x32x16_bf16 v[34:49], v[196:199], v[184:187], v[34:49]
	ds_read_b128 v[184:187], v133 offset:59904
	ds_read_b128 v[140:143], v133 offset:59936
	s_waitcnt lgkmcnt(1)
	v_mfma_f32_32x32x16_bf16 v[18:33], v[180:183], v[184:187], v[18:33]
	v_mfma_f32_32x32x16_bf16 v[2:17], v[196:199], v[184:187], v[2:17]
	v_mfma_f32_32x32x16_bf16 v[50:65], v[192:195], v[188:191], v[50:65]
	v_mfma_f32_32x32x16_bf16 v[34:49], v[200:203], v[188:191], v[34:49]
	s_cbranch_vccnz .Lhgw_skip_15
	s_waitcnt vmcnt(11)
	ds_write_b128 v128, v[90:93]
	s_waitcnt vmcnt(10)
	ds_write_b128 v129, v[94:97]
	s_waitcnt vmcnt(9)
	ds_write_b128 v128, v[98:101] offset:18432
	s_waitcnt vmcnt(8)
	ds_write_b128 v129, v[102:105] offset:18432
	s_waitcnt vmcnt(7)
	ds_write_b128 v130, v[106:109] offset:18432
	s_waitcnt vmcnt(6)
	ds_write_b128 v131, v[110:113] offset:18432
.Lhgw_skip_15:
	ds_read_b128 v[180:183], v138 offset:55360
	ds_read_b128 v[184:187], v133 offset:55360
	ds_read_b128 v[188:191], v133 offset:55392
	ds_read_b128 v[196:199], v138 offset:55392
	s_waitcnt lgkmcnt(4)
	v_mfma_f32_32x32x16_bf16 v[18:33], v[192:195], v[140:143], v[18:33]
	v_mfma_f32_32x32x16_bf16 v[2:17], v[200:203], v[140:143], v[2:17]
	ds_read_b128 v[192:195], v138 offset:59968
	ds_read_b128 v[140:143], v138 offset:60000
	s_waitcnt lgkmcnt(4)
	v_mfma_f32_32x32x16_bf16 v[50:65], v[180:183], v[184:187], v[50:65]
	s_waitcnt lgkmcnt(1)
	v_mfma_f32_32x32x16_bf16 v[34:49], v[192:195], v[184:187], v[34:49]
	ds_read_b128 v[184:187], v133 offset:59968
	ds_read_b128 v[144:147], v133 offset:60000
	s_waitcnt lgkmcnt(1)
	v_mfma_f32_32x32x16_bf16 v[18:33], v[180:183], v[184:187], v[18:33]
	v_mfma_f32_32x32x16_bf16 v[2:17], v[192:195], v[184:187], v[2:17]
	v_mfma_f32_32x32x16_bf16 v[50:65], v[196:199], v[188:191], v[50:65]
	v_mfma_f32_32x32x16_bf16 v[34:49], v[140:143], v[188:191], v[34:49]
	s_waitcnt lgkmcnt(0)
	v_mfma_f32_32x32x16_bf16 v[18:33], v[196:199], v[144:147], v[18:33]
	v_mfma_f32_32x32x16_bf16 v[2:17], v[140:143], v[144:147], v[2:17]
	s_branch .LBB0_1755
